# scan patch + per-XCD staggered start (blockIdx%8 x ~1.2us) of the in-proj and up GEMM phases
# baseline (speedup 1.0000x reference)
.LBB0_122:
	s_andn2_b64 vcc, exec, s[2:3]
	s_cbranch_vccnz .LBB0_269
	v_readlane_b32 s2, v252, 29
	v_readlane_b32 s3, v252, 30
	s_mov_b32 s6, 0
	v_mov_b32 v2, v0
	s_waitcnt vmcnt(8)
	v_mov_b32 v11, v0
	s_andn2_b64 vcc, exec, s[2:3]
	v_readfirstlane_b32 s12, v11
	s_cbranch_vccnz .LBB0_156
	v_readlane_b32 s100, v252, 0
	s_and_b32 s100, s100, 7
	s_cmp_eq_u32 s100, 0
	s_cbranch_scc1 .Lstg_done_in
.Lstg_loop_in:
	s_sleep 40
	s_sub_u32 s100, s100, 1
	s_cmp_lg_u32 s100, 0
	s_cbranch_scc1 .Lstg_loop_in
.Lstg_done_in:
	v_lshlrev_b32_e32 v2, 4, v11
	v_add_u32_e32 v3, 0x2000, v2
	v_ashrrev_i32_e32 v4, 31, v3
	v_lshrrev_b32_e32 v4, 22, v4
	v_add_u32_e32 v4, v3, v4
	v_ashrrev_i32_e32 v10, 10, v4
	v_mul_i32_i24_e32 v4, 0x400, v10
	v_sub_u32_e32 v3, v3, v4
	v_lshrrev_b32_e32 v4, 4, v3
	v_bitop3_b32 v3, v4, v3, 32 bitop3:0x6c
	v_readlane_b32 s2, v252, 19
	v_ashrrev_i32_e32 v4, 31, v3
	s_add_u32 s46, s2, s6
	v_readlane_b32 s2, v252, 20
	v_lshrrev_b32_e32 v4, 26, v4
	s_addc_u32 s47, s2, 0
	v_readlane_b32 s2, v252, 21
	v_add_u32_e32 v4, v3, v4
	s_waitcnt lgkmcnt(0)
	v_lshlrev_b32_e32 v5, 3, v10
	s_add_u32 s4, s2, s6
	v_readlane_b32 s2, v252, 22
	s_mul_i32 s30, s95, 0x2f00000
	s_waitcnt vmcnt(8)
	v_ashrrev_i32_e32 v12, 6, v4
	v_and_b32_e32 v5, -16, v5
	s_addc_u32 s5, s2, 0
	s_lshl_b64 s[2:3], s[30:31], 1
	v_add_u32_e32 v5, v12, v5
	s_add_u32 s48, s4, s2
	v_and_b32_e32 v6, 3, v12
	s_mov_b32 s2, 0x7ffe0
	v_lshrrev_b32_e32 v7, 2, v5
	v_lshlrev_b32_e32 v8, 1, v5
	v_and_b32_e32 v4, 0xc0, v4
	v_and_or_b32 v6, v5, s2, v6
	v_and_b32_e32 v7, 4, v7
	v_and_b32_e32 v8, 24, v8
	v_sub_u32_e32 v3, v3, v4
	v_or3_b32 v6, v6, v7, v8
	v_lshlrev_b32_e32 v7, 5, v10
	v_ashrrev_i16_sdwa v3, v229, sext(v3) dst_sel:DWORD dst_unused:UNUSED_PAD src0_sel:DWORD src1_sel:BYTE_0
	v_and_b32_e32 v7, 32, v7
	v_bfe_i32 v13, v3, 0, 16
	v_add_lshl_u32 v3, v7, v13, 1
	v_lshl_add_u32 v132, v6, 13, v3
	v_lshl_add_u32 v134, v5, 13, v3
	v_bfe_i32 v3, v11, 27, 1
	v_lshrrev_b32_e32 v3, 22, v3
	v_add_u32_e32 v3, v2, v3
	v_and_b32_e32 v3, 0xfffffc00, v3
	v_sub_u32_e32 v2, v2, v3
	v_lshrrev_b32_e32 v3, 4, v2
	v_bitop3_b32 v3, v3, v2, 32 bitop3:0x6c
	v_ashrrev_i32_e32 v2, 31, v2
	v_lshrrev_b32_e32 v2, 26, v2
	v_add_u32_e32 v2, v3, v2
	v_ashrrev_i32_e32 v14, 6, v2
	v_ashrrev_i32_e32 v2, 31, v11
	v_lshrrev_b32_e32 v2, 26, v2
	v_add_u32_e32 v2, v11, v2
	v_ashrrev_i32_e32 v15, 6, v2
	v_lshlrev_b32_e32 v2, 3, v15
	v_and_b32_e32 v2, -16, v2
	v_add_u32_e32 v2, v14, v2
	v_and_b32_e32 v4, 3, v14
	v_lshrrev_b32_e32 v5, 2, v2
	v_lshlrev_b32_e32 v6, 1, v2
	v_and_or_b32 v4, v2, s2, v4
	v_and_b32_e32 v5, 4, v5
	v_and_b32_e32 v6, 24, v6
	v_or3_b32 v4, v4, v5, v6
	v_mul_i32_i24_e32 v6, 64, v14
	s_addc_u32 s49, s5, s3
	s_ashr_i32 s16, s12, 6
	v_sub_u32_e32 v3, v3, v6
	s_ashr_i32 s13, s12, 8
	s_lshl_b32 s50, s16, 10
	v_lshlrev_b32_e32 v5, 5, v15
	v_ashrrev_i16_sdwa v3, v229, sext(v3) dst_sel:DWORD dst_unused:UNUSED_PAD src0_sel:DWORD src1_sel:BYTE_0
	v_readlane_b32 s2, v254, 35
	v_and_b32_e32 v5, 32, v5
	v_bfe_i32 v16, v3, 0, 16
	v_readlane_b32 s3, v254, 36
	s_add_u32 s36, s48, s2
	v_add_lshl_u32 v3, v5, v16, 1
	s_addc_u32 s37, s49, s3
	s_add_i32 s51, s50, 0
	v_lshl_add_u32 v130, v4, 13, v3
	s_add_i32 m0, s51, 0x10000
	v_lshl_add_u32 v136, v2, 13, v3
	global_load_lds_dwordx4 v130, s[36:37]
	s_add_i32 m0, s51, 0x12000
	s_add_u32 s2, s36, 0x100000
	global_load_lds_dwordx4 v132, s[36:37]
	s_addc_u32 s3, s37, 0
	s_add_i32 m0, s51, 0x14000
	v_mov_b32_e32 v133, v131
	global_load_lds_dwordx4 v130, s[2:3]
	s_add_i32 m0, s51, 0x16000
	v_mov_b32_e32 v137, v131
	global_load_lds_dwordx4 v132, s[2:3]
	v_readlane_b32 s2, v254, 44
	v_readlane_b32 s3, v254, 45
	s_add_u32 s34, s46, s2
	s_addc_u32 s35, s47, s3
	s_add_i32 s52, s51, 0x2000
	s_mov_b32 m0, s51
	s_add_u32 s2, s34, 0x100000
	global_load_lds_dwordx4 v136, s[34:35]
	s_mov_b32 m0, s52
	s_addc_u32 s3, s35, 0
	s_add_i32 s53, s51, 0x4000
	global_load_lds_dwordx4 v134, s[34:35]
	s_mov_b32 m0, s53
	s_add_i32 s54, s51, 0x6000
	global_load_lds_dwordx4 v136, s[2:3]
	s_mov_b32 m0, s54
	v_mov_b32_e32 v135, v131
	global_load_lds_dwordx4 v134, s[2:3]
	s_cmp_eq_u32 s13, 1
	v_lshl_add_u64 v[8:9], s[36:37], 0, v[130:131]
	v_lshl_add_u64 v[6:7], s[36:37], 0, v[132:133]
	v_lshl_add_u64 v[2:3], s[34:35], 0, v[136:137]
	s_cselect_b64 s[2:3], -1, 0
	s_cmp_lg_u32 s13, 1
	v_lshl_add_u64 v[4:5], s[34:35], 0, v[134:135]
	s_cbranch_scc1 .LBB0_126
	s_barrier

.LBB0_1014:
	s_andn2_b64 vcc, exec, s[2:3]
	s_cbranch_vccnz .LBB0_1157
	v_readlane_b32 s2, v254, 15
	v_readlane_b32 s3, v254, 16
	s_mov_b32 s12, 0
	v_mov_b32 v2, v0
	s_waitcnt vmcnt(8)
	v_mov_b32 v13, v0
	s_andn2_b64 vcc, exec, s[2:3]
	v_readfirstlane_b32 s16, v13
	s_cbranch_vccnz .LBB0_1044
	v_readlane_b32 s100, v252, 0
	s_and_b32 s100, s100, 7
	s_cmp_eq_u32 s100, 0
	s_cbranch_scc1 .Lstg_done_up

.Lstg_done_up:
	v_lshlrev_b32_e32 v2, 4, v13
	v_add_u32_e32 v3, 0x2000, v2
	v_ashrrev_i32_e32 v4, 31, v3
	v_lshrrev_b32_e32 v4, 22, v4
	v_add_u32_e32 v4, v3, v4
	v_ashrrev_i32_e32 v10, 10, v4
	v_mul_i32_i24_e32 v4, 0x400, v10
	v_readlane_b32 s2, v252, 19
	v_sub_u32_e32 v3, v3, v4
	s_add_u32 s60, s2, s12
	v_readlane_b32 s2, v252, 20
	v_lshrrev_b32_e32 v4, 4, v3
	s_addc_u32 s61, s2, 0
	v_readlane_b32 s2, v254, 9
	v_bitop3_b32 v3, v4, v3, 32 bitop3:0x6c
	s_add_u32 s2, s2, s12
	v_readlane_b32 s3, v254, 10
	v_ashrrev_i32_e32 v4, 31, v3
	s_addc_u32 s3, s3, 0
	s_mul_i32 s4, s95, 0xac00000
	v_lshrrev_b32_e32 v4, 26, v4
	s_add_u32 s62, s2, s4
	v_add_u32_e32 v4, v3, v4
	s_waitcnt lgkmcnt(0)
	v_lshlrev_b32_e32 v5, 3, v10
	s_addc_u32 s63, s3, 0
	s_ashr_i32 s13, s12, 31
	v_ashrrev_i32_e32 v11, 6, v4
	v_and_b32_e32 v5, -16, v5
	s_lshl_b64 s[2:3], s[12:13], 3
	v_readlane_b32 s4, v252, 3
	v_add_u32_e32 v5, v11, v5
	s_add_u32 s4, s4, s2
	v_and_b32_e32 v6, 3, v11
	s_mov_b32 s2, 0x7ffe0
	v_lshrrev_b32_e32 v7, 2, v5
	v_lshlrev_b32_e32 v8, 1, v5
	v_and_b32_e32 v4, 0xc0, v4
	v_and_or_b32 v6, v5, s2, v6
	v_and_b32_e32 v7, 4, v7
	v_and_b32_e32 v8, 24, v8
	v_sub_u32_e32 v3, v3, v4
	v_or3_b32 v6, v6, v7, v8
	v_lshlrev_b32_e32 v7, 5, v10
	v_ashrrev_i16_sdwa v3, v229, sext(v3) dst_sel:DWORD dst_unused:UNUSED_PAD src0_sel:DWORD src1_sel:BYTE_0
	v_and_b32_e32 v7, 32, v7
	v_bfe_i32 v12, v3, 0, 16
	v_add_lshl_u32 v3, v7, v12, 1
	v_lshl_add_u32 v216, v6, 13, v3
	v_lshl_add_u32 v218, v5, 13, v3
	v_bfe_i32 v3, v13, 27, 1
	v_lshrrev_b32_e32 v3, 22, v3
	v_add_u32_e32 v3, v2, v3
	v_and_b32_e32 v3, 0xfffffc00, v3
	v_sub_u32_e32 v2, v2, v3
	v_lshrrev_b32_e32 v3, 4, v2
	v_bitop3_b32 v3, v3, v2, 32 bitop3:0x6c
	v_ashrrev_i32_e32 v2, 31, v2
	v_lshrrev_b32_e32 v2, 26, v2
	v_add_u32_e32 v2, v3, v2
	v_ashrrev_i32_e32 v14, 6, v2
	v_ashrrev_i32_e32 v2, 31, v13
	v_lshrrev_b32_e32 v2, 26, v2
	v_add_u32_e32 v2, v13, v2
	v_ashrrev_i32_e32 v15, 6, v2
	v_lshlrev_b32_e32 v2, 3, v15
	v_and_b32_e32 v2, -16, v2
	v_add_u32_e32 v2, v14, v2
	v_and_b32_e32 v4, 3, v14
	v_lshrrev_b32_e32 v5, 2, v2
	v_lshlrev_b32_e32 v6, 1, v2
	v_and_or_b32 v4, v2, s2, v4
	v_and_b32_e32 v5, 4, v5
	v_and_b32_e32 v6, 24, v6
	v_readlane_b32 s5, v252, 4
	v_or3_b32 v4, v4, v5, v6
	v_mul_i32_i24_e32 v6, 64, v14
	s_addc_u32 s5, s5, s3
	s_ashr_i32 s17, s16, 6
	v_sub_u32_e32 v3, v3, v6
	s_ashr_i32 s26, s16, 8
	s_lshl_b32 s66, s17, 10
	v_lshlrev_b32_e32 v5, 5, v15
	v_ashrrev_i16_sdwa v3, v229, sext(v3) dst_sel:DWORD dst_unused:UNUSED_PAD src0_sel:DWORD src1_sel:BYTE_0
	v_readlane_b32 s2, v254, 38
	v_and_b32_e32 v5, 32, v5
	v_bfe_i32 v16, v3, 0, 16
	v_readlane_b32 s3, v254, 39
	s_add_u32 s46, s62, s2
	v_add_lshl_u32 v3, v5, v16, 1
	s_addc_u32 s47, s63, s3
	s_add_i32 s67, s66, 0
	v_lshl_add_u32 v130, v4, 13, v3
	s_add_i32 m0, s67, 0x10000
	v_lshl_add_u32 v220, v2, 13, v3
	global_load_lds_dwordx4 v130, s[46:47]
	s_add_i32 m0, s67, 0x12000
	s_add_u32 s2, s46, 0x100000
	global_load_lds_dwordx4 v216, s[46:47]
	s_addc_u32 s3, s47, 0
	s_add_i32 m0, s67, 0x14000
	s_load_dwordx2 s[8:9], s[4:5], 0x68
	global_load_lds_dwordx4 v130, s[2:3]
	s_add_i32 m0, s67, 0x16000
	v_mov_b32_e32 v217, v131
	global_load_lds_dwordx4 v216, s[2:3]
	v_readlane_b32 s2, v254, 48
	v_readlane_b32 s3, v254, 49
	s_add_u32 s2, s60, s2
	s_addc_u32 s3, s61, s3
	s_add_i32 s68, s67, 0x2000
	s_mov_b32 m0, s67
	s_add_u32 s6, s2, 0x100000
	global_load_lds_dwordx4 v220, s[2:3]
	s_mov_b32 m0, s68
	s_addc_u32 s7, s3, 0
	s_add_i32 s69, s67, 0x4000
	global_load_lds_dwordx4 v218, s[2:3]
	s_mov_b32 m0, s69
	s_add_i32 s70, s67, 0x6000
	global_load_lds_dwordx4 v220, s[6:7]
	s_mov_b32 m0, s70
	v_mov_b32_e32 v221, v131
	global_load_lds_dwordx4 v218, s[6:7]
	v_mov_b32_e32 v219, v131
	s_cmp_eq_u32 s26, 1
	v_lshl_add_u64 v[8:9], s[46:47], 0, v[130:131]
	v_lshl_add_u64 v[6:7], s[46:47], 0, v[216:217]
	v_lshl_add_u64 v[2:3], s[2:3], 0, v[220:221]
	s_cselect_b64 s[4:5], -1, 0
	s_cmp_lg_u32 s26, 1
	v_lshl_add_u64 v[4:5], s[2:3], 0, v[218:219]
	s_cbranch_scc1 .LBB0_1018
	s_barrier

	.amdhsa_kernel _Z10hybrid_fwd4Args
		.amdhsa_group_segment_fixed_size 0
		.amdhsa_private_segment_fixed_size 0
		.amdhsa_kernarg_size 416
		.amdhsa_user_sgpr_count 2
		.amdhsa_user_sgpr_dispatch_ptr 0
		.amdhsa_user_sgpr_queue_ptr 0
		.amdhsa_user_sgpr_kernarg_segment_ptr 1
		.amdhsa_user_sgpr_dispatch_id 0
		.amdhsa_user_sgpr_kernarg_preload_length 0
		.amdhsa_user_sgpr_kernarg_preload_offset 0
		.amdhsa_user_sgpr_private_segment_size 0
		.amdhsa_uses_dynamic_stack 0
		.amdhsa_enable_private_segment 0
		.amdhsa_system_sgpr_workgroup_id_x 1
		.amdhsa_system_sgpr_workgroup_id_y 0
		.amdhsa_system_sgpr_workgroup_id_z 0
		.amdhsa_system_sgpr_workgroup_info 0
		.amdhsa_system_vgpr_workitem_id 0
		.amdhsa_next_free_vgpr 256
		.amdhsa_next_free_sgpr 101
		.amdhsa_accum_offset 256
		.amdhsa_reserve_vcc 1
		.amdhsa_float_round_mode_32 0
		.amdhsa_float_round_mode_16_64 0
		.amdhsa_float_denorm_mode_32 3
		.amdhsa_float_denorm_mode_16_64 3
		.amdhsa_dx10_clamp 1
		.amdhsa_ieee_mode 1
		.amdhsa_fp16_overflow 0
		.amdhsa_tg_split 0
		.amdhsa_exception_fp_ieee_invalid_op 0
		.amdhsa_exception_fp_denorm_src 0
		.amdhsa_exception_fp_ieee_div_zero 0
		.amdhsa_exception_fp_ieee_overflow 0
		.amdhsa_exception_fp_ieee_underflow 0
		.amdhsa_exception_fp_ieee_inexact 0
		.amdhsa_exception_int_div_zero 0
	.end_amdhsa_kernel

amdhsa.kernels:
  - .agpr_count:     0
    .args:
      - .offset:         0
        .size:           160
        .value_kind:     by_value
      - .offset:         160
        .size:           4
        .value_kind:     hidden_block_count_x
      - .offset:         164
        .size:           4
        .value_kind:     hidden_block_count_y
      - .offset:         168
        .size:           4
        .value_kind:     hidden_block_count_z
      - .offset:         172
        .size:           2
        .value_kind:     hidden_group_size_x
      - .offset:         174
        .size:           2
        .value_kind:     hidden_group_size_y
      - .offset:         176
        .size:           2
        .value_kind:     hidden_group_size_z
      - .offset:         178
        .size:           2
        .value_kind:     hidden_remainder_x
      - .offset:         180
        .size:           2
        .value_kind:     hidden_remainder_y
      - .offset:         182
        .size:           2
        .value_kind:     hidden_remainder_z
      - .offset:         200
        .size:           8
        .value_kind:     hidden_global_offset_x
      - .offset:         208
        .size:           8
        .value_kind:     hidden_global_offset_y
      - .offset:         216
        .size:           8
        .value_kind:     hidden_global_offset_z
      - .offset:         224
        .size:           2
        .value_kind:     hidden_grid_dims
      - .offset:         280
        .size:           4
        .value_kind:     hidden_dynamic_lds_size
    .group_segment_fixed_size: 0
    .kernarg_segment_align: 8
    .kernarg_segment_size: 416
    .language:       OpenCL C
    .language_version:
      - 2
      - 0
    .max_flat_workgroup_size: 512
    .name:           _Z10hybrid_fwd4Args
    .private_segment_fixed_size: 0
    .sgpr_count:     107
    .sgpr_spill_count: 232
    .symbol:         _Z10hybrid_fwd4Args.kd
    .uniform_work_group_size: 1
    .uses_dynamic_stack: false
    .vgpr_count:     256
    .vgpr_spill_count: 0
    .wavefront_size: 64
